# stack13 + attention epilogue: the 16 row-sum values read with 8 ds_read2 issued at once (was 7 exposed LDS round trips)
# baseline (speedup 1.0000x reference)
; #define SBAR() __builtin_amdgcn_sched_barrier(0)
; #define PKW(P, B) cvtpk_h(P[B], P[B + 1])
; #define PKW(P, B) cvtpk_h(P[B], P[B + 1])
; template <int THRL, bool FIXM> __device__ __forceinline__ bool attn_unit(const h16* Qrows, const h16* __restrict__ Kh, const h16* __restrict__ Vh, const int NT, h16* Yrows, const h16* BZrows, char* shm, const int tid, const float mfix, ...
;     ...
;   { float sacc = pB0[0] + pB0[1]; _Pragma("unroll") for (int r = 2; r < 16; ++r) sacc += pB0[r]; _Pragma("unroll") for (int r = 0; r < 16; ++r) sacc += pB1[r]; l_reg += sacc;
;     pw0 = (u32x4){PKW(pB0, 0), PKW(pB0, 2), PKW(pB0, 4), PKW(pB0, 6)}; pw1 = (u32x4){PKW(pB0, 8), PKW(pB0, 10), PKW(pB0, 12), PKW(pB0, 14)}; pw2 = (u32x4){PKW(pB1, 0), PKW(pB1, 2), PKW(pB1, 4), PKW(pB1, 6)}; pw3 = (u32x4){PKW(pB1, 8), PKW(pB1, 10), PKW(pB1, 12), PKW(pB1, 14)};
;     SBAR(); pv(o, vb0 + sl_cur, __builtin_bit_cast(s16x8, pw0), __builtin_bit_cast(s16x8, pw1), __builtin_bit_cast(s16x8, pw2), __builtin_bit_cast(s16x8, pw3)); }
.LBB0_124:
	s_and_b32 s12, s29, 0x3fffffc0
	s_lshl_b32 s12, s12, 2
	s_add_i32 s14, s41, s12
	v_add_u32_e32 v0, s51, v233
	ds_read_b64_tr_b16 v[52:53], v0 offset:24576
	ds_read_b64_tr_b16 v[54:55], v0 offset:25088
	v_add_f32_e32 v51, v82, v83
	v_add_f32_e32 v51, v84, v51
	v_add_f32_e32 v51, v85, v51
	v_add_f32_e32 v51, v86, v51
	v_add_f32_e32 v51, v87, v51
	v_cvt_pk_f16_f32 v160, v82, v83
	v_cvt_pk_f16_f32 v161, v84, v85
	s_waitcnt lgkmcnt(9)
	v_mfma_f32_32x32x16_f16 v[98:113], v[192:195], v[144:147], v[2:17]
	ds_read_b64_tr_b16 v[56:57], v0 offset:28672
	ds_read_b64_tr_b16 v[58:59], v0 offset:29184
	s_waitcnt lgkmcnt(10)
	v_mfma_f32_32x32x16_f16 v[2:17], v[188:191], v[144:147], v[2:17]
	v_add_f32_e32 v51, v88, v51
	v_add_f32_e32 v51, v89, v51
	v_add_f32_e32 v51, v90, v51
	v_add_f32_e32 v51, v91, v51
	v_cvt_pk_f16_f32 v162, v86, v87
	v_cvt_pk_f16_f32 v163, v88, v89
	ds_read_b64_tr_b16 v[60:61], v0 offset:25600
	ds_read_b64_tr_b16 v[62:63], v0 offset:26112
	v_add_f32_e32 v51, v92, v51
	v_add_f32_e32 v51, v93, v51
	v_add_f32_e32 v51, v94, v51
	v_add_f32_e32 v51, v95, v51
	v_cvt_pk_f16_f32 v156, v90, v91
	v_cvt_pk_f16_f32 v157, v92, v93
	s_waitcnt lgkmcnt(11)
	v_mfma_f32_32x32x16_f16 v[98:113], v[184:187], v[140:143], v[98:113]
	ds_read_b64_tr_b16 v[82:83], v0 offset:29696
	ds_read_b64_tr_b16 v[84:85], v0 offset:30208
	s_waitcnt lgkmcnt(12)
	v_mfma_f32_32x32x16_f16 v[2:17], v[180:183], v[140:143], v[2:17]
	v_add_f32_e32 v51, v96, v51
	v_add_f32_e32 v51, v97, v51
	v_add_f32_e32 v51, v66, v51
	v_add_f32_e32 v51, v67, v51
	v_cvt_pk_f16_f32 v158, v94, v95
	v_cvt_pk_f16_f32 v159, v96, v97
	ds_read_b64_tr_b16 v[86:87], v0 offset:26624
	ds_read_b64_tr_b16 v[88:89], v0 offset:27136
	v_add_f32_e32 v51, v68, v51
	v_add_f32_e32 v51, v69, v51
	v_add_f32_e32 v51, v70, v51
	v_add_f32_e32 v51, v71, v51
	v_cvt_pk_f16_f32 v152, v66, v67
	v_cvt_pk_f16_f32 v153, v68, v69
	s_waitcnt lgkmcnt(13)
	v_mfma_f32_32x32x16_f16 v[98:113], v[176:179], v[136:139], v[98:113]
	ds_read_b64_tr_b16 v[64:65], v0 offset:30720
	ds_read_b64_tr_b16 v[66:67], v0 offset:31232
	s_waitcnt lgkmcnt(14)
	v_mfma_f32_32x32x16_f16 v[2:17], v[172:175], v[136:139], v[2:17]
	v_add_f32_e32 v51, v72, v51
	v_add_f32_e32 v51, v73, v51
	v_add_f32_e32 v51, v74, v51
	v_add_f32_e32 v51, v75, v51
	v_cvt_pk_f16_f32 v154, v70, v71
	v_cvt_pk_f16_f32 v155, v72, v73
	ds_read_b64_tr_b16 v[68:69], v0 offset:27648
	ds_read_b64_tr_b16 v[70:71], v0 offset:28160
	v_add_f32_e32 v51, v76, v51
	v_add_f32_e32 v51, v77, v51
	v_add_f32_e32 v51, v78, v51
	v_add_f32_e32 v51, v79, v51
	v_cvt_pk_f16_f32 v148, v74, v75
	v_cvt_pk_f16_f32 v149, v76, v77
	s_waitcnt lgkmcnt(14)
	v_mfma_f32_32x32x16_f16 v[98:113], v[168:171], v[132:135], v[98:113]
	ds_read_b64_tr_b16 v[72:73], v0 offset:31744
	ds_read_b64_tr_b16 v[74:75], v0 offset:32256
	v_mfma_f32_32x32x16_f16 v[2:17], v[164:167], v[132:135], v[2:17]
	v_add_f32_e32 v0, v80, v51
	v_add_f32_e32 v0, v81, v0
	v_add_f32_e32 v0, 0, v0
	v_cvt_pk_f16_f32 v150, v78, v79
	v_cvt_pk_f16_f32 v151, v80, v81
	s_waitcnt lgkmcnt(14)
	v_mfma_f32_32x32x16_f16 v[18:33], v[160:163], v[52:55], v[18:33]
	s_nop 1
	v_exp_f32_e32 v98, v98
	v_exp_f32_e32 v99, v99
	v_exp_f32_e32 v100, v100
	v_exp_f32_e32 v101, v101
	s_waitcnt lgkmcnt(12)
	v_mfma_f32_32x32x16_f16 v[34:49], v[160:163], v[56:59], v[34:49]
	v_exp_f32_e32 v102, v102
	v_exp_f32_e32 v103, v103
	v_exp_f32_e32 v104, v104
	v_exp_f32_e32 v105, v105
	s_waitcnt lgkmcnt(10)
	v_mfma_f32_32x32x16_f16 v[18:33], v[156:159], v[60:63], v[18:33]
	v_exp_f32_e32 v106, v106
	v_exp_f32_e32 v107, v107
	v_exp_f32_e32 v108, v108
	v_exp_f32_e32 v109, v109
	s_waitcnt lgkmcnt(8)
	v_mfma_f32_32x32x16_f16 v[34:49], v[156:159], v[82:85], v[34:49]
	v_exp_f32_e32 v110, v110
	v_exp_f32_e32 v111, v111
	v_exp_f32_e32 v112, v112
	v_exp_f32_e32 v113, v113
	s_waitcnt lgkmcnt(6)
	v_mfma_f32_32x32x16_f16 v[18:33], v[152:155], v[86:89], v[18:33]
	v_exp_f32_e32 v2, v2
	v_exp_f32_e32 v3, v3
	v_exp_f32_e32 v4, v4
	v_exp_f32_e32 v5, v5
	s_waitcnt lgkmcnt(4)
	v_mfma_f32_32x32x16_f16 v[34:49], v[152:155], v[64:67], v[34:49]
	v_exp_f32_e32 v6, v6
	v_exp_f32_e32 v7, v7
	v_exp_f32_e32 v8, v8
	v_exp_f32_e32 v9, v9
	s_waitcnt lgkmcnt(2)
	v_mfma_f32_32x32x16_f16 v[18:33], v[148:151], v[68:71], v[18:33]
	v_exp_f32_e32 v10, v10
	v_exp_f32_e32 v11, v11
	v_exp_f32_e32 v12, v12
	v_exp_f32_e32 v13, v13
	s_waitcnt lgkmcnt(0)
	v_mfma_f32_32x32x16_f16 v[34:49], v[148:151], v[72:75], v[34:49]
	v_exp_f32_e32 v14, v14
	v_exp_f32_e32 v15, v15
	v_exp_f32_e32 v16, v16
	v_exp_f32_e32 v17, v17
	v_add_f32_e32 v51, v98, v99
	v_add_f32_e32 v51, v100, v51
	v_add_f32_e32 v51, v101, v51
	v_add_f32_e32 v51, v102, v51
	v_add_f32_e32 v51, v103, v51
	v_add_f32_e32 v51, v104, v51
	v_add_f32_e32 v51, v105, v51
	v_add_f32_e32 v51, v106, v51
	v_add_f32_e32 v51, v107, v51
	v_add_f32_e32 v51, v108, v51
	v_add_f32_e32 v51, v109, v51
	v_add_f32_e32 v51, v110, v51
	v_add_f32_e32 v51, v111, v51
	v_add_f32_e32 v51, v112, v51
	v_add_f32_e32 v82, v113, v51
	v_add_f32_e32 v83, v50, v0
	v_cvt_pk_f16_f32 v50, v98, v99
	v_cvt_pk_f16_f32 v51, v100, v101
	v_cvt_pk_f16_f32 v52, v102, v103
	v_cvt_pk_f16_f32 v53, v104, v105
	v_cvt_pk_f16_f32 v54, v106, v107
	v_cvt_pk_f16_f32 v55, v108, v109
	v_cvt_pk_f16_f32 v56, v110, v111
	v_cvt_pk_f16_f32 v57, v112, v113
	v_cvt_pk_f16_f32 v66, v2, v3
	v_cvt_pk_f16_f32 v67, v4, v5
	v_cvt_pk_f16_f32 v68, v6, v7
	v_cvt_pk_f16_f32 v69, v8, v9
	v_cvt_pk_f16_f32 v70, v10, v11
	v_cvt_pk_f16_f32 v71, v12, v13
	v_cvt_pk_f16_f32 v72, v14, v15
	v_cvt_pk_f16_f32 v73, v16, v17
	v_or3_b32 v0, v243, v232, v231
	s_add_i32 s12, s77, s17
	v_add_u32_e32 v0, s12, v0
	ds_read_b64_tr_b16 v[58:59],v0 offset:0
	ds_read_b64_tr_b16 v[60:61],v0 offset:512
	ds_read_b64_tr_b16 v[62:63],v0 offset:1024
	ds_read_b64_tr_b16 v[64:65],v0 offset:1536
	ds_read_b64_tr_b16 v[74:75],v0 offset:2048
	ds_read_b64_tr_b16 v[76:77],v0 offset:2560
	ds_read_b64_tr_b16 v[78:79],v0 offset:3072
	ds_read_b64_tr_b16 v[80:81],v0 offset:3584
	s_waitcnt lgkmcnt(0)
; #define GAS __attribute__((address_space(1)))
; __device__ __forceinline__ int crow(int r, int hi) { return (r & 3) + 8 * (r >> 2) + 4 * hi; }
; #define SBAR() __builtin_amdgcn_sched_barrier(0)
; __device__ __forceinline__ void pv(f32x16* o, int vb, s16x8 pa0, s16x8 pa1, s16x8 pa2, s16x8 pa3) {
;     ...
;       asm volatile("ds_read_b64_tr_b16 %0,%1 offset:%c2" : "=&v"(lo[ks]) : "v"(vb), "i"(d0 * 4096 + ks * 1024) : "memory");
;       asm volatile("ds_read_b64_tr_b16 %0,%1 offset:%c2" : "=&v"(hi[ks]) : "v"(vb), "i"(d0 * 4096 + ks * 1024 + 512) : "memory"); }
;     asm volatile("s_waitcnt lgkmcnt(0)" ::: "memory"); SBAR();
;     ...
;     o[d0] = __builtin_amdgcn_mfma_f32_32x32x16_f16(H8(pa0), H8(PK(0)), o[d0], 0, 0, 0);
;     o[d0] = __builtin_amdgcn_mfma_f32_32x32x16_f16(H8(pa1), H8(PK(1)), o[d0], 0, 0, 0);
;     o[d0] = __builtin_amdgcn_mfma_f32_32x32x16_f16(H8(pa2), H8(PK(2)), o[d0], 0, 0, 0);
;     o[d0] = __builtin_amdgcn_mfma_f32_32x32x16_f16(H8(pa3), H8(PK(3)), o[d0], 0, 0, 0);
; template <int THRL, bool FIXM> __device__ __forceinline__ bool attn_unit(const h16* Qrows, const h16* __restrict__ Kh, const h16* __restrict__ Vh, const int NT, h16* Yrows, const h16* BZrows, char* shm, const int tid, const float mfix, ...
;     ...
;   { const h16* Zw0 = BZrows + (long)(wid * QBLK) * ZP;
; #pragma unroll
;     for (int i = 0; i < 4; ++i) zg[i] = *(const GAS h16x8*)(Zw0 + (long)(i * 8 + (lane >> 3)) * ZP + (lane & 7) * 8); }
;     ...
;   { auto rr = __builtin_amdgcn_permlane32_swap(__float_as_uint(l_reg), __float_as_uint(l_reg), false, false); l_reg = __uint_as_float(rr[0]) + __uint_as_float(rr[1]); }
;   if (hi == 0) wsf[32 + r32] = l_reg; asm volatile("s_waitcnt lgkmcnt(0)" ::: "memory");
;   float rli[16];
; #pragma unroll
;   for (int r = 0; r < 16; ++r) rli[r] = __builtin_amdgcn_rcpf(wsf[32 + crow(r, hi)]);
;   h16* Yw = Yrows + (long)(wid * QBLK) * YP;
;   { h16* stg = (h16*)(shm + LDS_OST) + wid * 2048;
; #pragma unroll
;     for (int r = 0; r < 16; ++r) { const int orow = crow(r, hi);
; #pragma unroll
;       for (int d0 = 0; d0 < 2; ++d0) stg[orow * 64 + d0 * 32 + r32] = (h16)(o[d0][r] * rli[r]); }
	s_nop 0
	v_mfma_f32_32x32x16_f16 v[18:33], v[50:53], v[58:61], v[18:33]
	ds_read_b64_tr_b16 v[58:59],v0 offset:4096
	ds_read_b64_tr_b16 v[60:61],v0 offset:4608
	v_mfma_f32_32x32x16_f16 v[18:33], v[54:57], v[62:65], v[18:33]
	ds_read_b64_tr_b16 v[62:63],v0 offset:5120
	ds_read_b64_tr_b16 v[64:65],v0 offset:5632
	v_mfma_f32_32x32x16_f16 v[18:33], v[66:69], v[74:77], v[18:33]
	ds_read_b64_tr_b16 v[74:75],v0 offset:6144
	ds_read_b64_tr_b16 v[76:77],v0 offset:6656
	v_mfma_f32_32x32x16_f16 v[18:33], v[70:73], v[78:81], v[18:33]
	ds_read_b64_tr_b16 v[78:79],v0 offset:7168
	ds_read_b64_tr_b16 v[80:81],v0 offset:7680
	s_waitcnt lgkmcnt(0)
	v_mfma_f32_32x32x16_f16 v[34:49], v[50:53], v[58:61], v[34:49]
	s_lshl_b64 s[12:13], s[24:25], 1
	s_add_u32 s12, s82, s12
	v_and_b32_e32 v0, 56, v131
	s_addc_u32 s13, s81, s13
	v_and_b32_e32 v52, 0xe00, v230
	v_lshlrev_b32_e32 v0, 1, v0
	v_lshl_add_u64 v[50:51], s[12:13], 0, v[0:1]
	v_lshlrev_b32_e32 v52, 1, v52
	v_mov_b32_e32 v53, v1
	v_lshl_add_u64 v[50:51], v[50:51], 0, v[52:53]
	s_movk_i32 s12, 0x2000
	v_add_co_u32_e32 v52, vcc, s12, v50
	s_movk_i32 s12, 0x4000
	s_nop 0
	v_addc_co_u32_e32 v53, vcc, 0, v51, vcc
	v_mfma_f32_32x32x16_f16 v[34:49], v[54:57], v[62:65], v[34:49]
	global_load_dwordx4 v[62:65], v[50:51], off
	global_load_dwordx4 v[58:61], v[52:53], off
	v_add_co_u32_e32 v52, vcc, s12, v50
	v_add_f32_e32 v2, v2, v82
	s_nop 0
	v_addc_co_u32_e32 v53, vcc, 0, v51, vcc
	v_add_co_u32_e32 v50, vcc, s90, v50
	v_add_f32_e32 v2, v3, v2
	s_nop 0
	v_addc_co_u32_e32 v51, vcc, 0, v51, vcc
	global_load_dwordx4 v[54:57], v[52:53], off
	s_nop 0
	global_load_dwordx4 v[50:53], v[50:51], off
	v_add_f32_e32 v2, v4, v2
	v_mfma_f32_32x32x16_f16 v[34:49], v[66:69], v[74:77], v[34:49]
	v_add_f32_e32 v2, v5, v2
	v_add_f32_e32 v2, v6, v2
	v_add_f32_e32 v2, v7, v2
	v_add_f32_e32 v2, v8, v2
	v_add_f32_e32 v2, v9, v2
	v_add_f32_e32 v2, v10, v2
	v_add_f32_e32 v2, v11, v2
	v_add_f32_e32 v2, v12, v2
	v_mfma_f32_32x32x16_f16 v[34:49], v[70:73], v[78:81], v[34:49]
	v_add_f32_e32 v2, v13, v2
	v_add_f32_e32 v2, v14, v2
	v_add_f32_e32 v2, v15, v2
	v_add_f32_e32 v2, v16, v2
	v_add_f32_e32 v2, v17, v2
	v_add_f32_e32 v2, v83, v2
	v_mov_b32_e32 v3, v2
	s_nop 1
	v_permlane32_swap_b32_e32 v2, v3
	v_cmp_gt_u32_e32 vcc, 32, v249
	s_and_saveexec_b64 s[12:13], vcc
	v_lshl_add_u32 v4, v250, 2, s14
	v_add_f32_e32 v2, v2, v3
	ds_write_b32 v4, v2 offset:49280
	s_or_b64 exec, exec, s[12:13]
	v_lshl_add_u32 v4, v248, 4, s14
	s_waitcnt lgkmcnt(0)
	v_add_u32_e32 v2, 0xc080, v4
	ds_read2_b32 v[164:165], v2 offset1:1
	ds_read2_b32 v[166:167], v2 offset0:2 offset1:3
	ds_read2_b32 v[168:169], v2 offset0:8 offset1:9
	ds_read2_b32 v[170:171], v2 offset0:10 offset1:11
	ds_read2_b32 v[172:173], v2 offset0:16 offset1:17
	ds_read2_b32 v[174:175], v2 offset0:18 offset1:19
	ds_read2_b32 v[176:177], v2 offset0:24 offset1:25
	ds_read2_b32 v[178:179], v2 offset0:26 offset1:27
	s_lshl_b32 s12, s16, 12
	s_add_i32 s12, s41, s12
	v_lshlrev_b32_e32 v67, 1, v250
	s_lshl_b64 s[10:11], s[10:11], 11
	s_add_u32 s10, s79, s10
	s_addc_u32 s11, s80, s11
	s_mov_b32 s51, 0x41000000
	s_waitcnt lgkmcnt(0)
	v_rcp_f32_e32 v5, v164
	v_rcp_f32_e32 v6, v165
	v_rcp_f32_e32 v7, v166
	v_rcp_f32_e32 v8, v167
	v_rcp_f32_e32 v9, v168
	v_rcp_f32_e32 v10, v169
	v_rcp_f32_e32 v11, v170
	v_rcp_f32_e32 v12, v171
	v_rcp_f32_e32 v13, v172
	v_rcp_f32_e32 v14, v173
	v_rcp_f32_e32 v15, v174
	v_rcp_f32_e32 v16, v175
	v_rcp_f32_e32 v17, v176
	v_fma_mixlo_f16 v4, v18, v5, 0
	v_lshlrev_b32_e32 v18, 1, v240
	v_add3_u32 v18, s12, v18, v67
	ds_write_b16 v18, v4 offset:51200
	v_fma_mixlo_f16 v4, v34, v5, 0
	ds_write_b16 v18, v4 offset:51264
	v_fma_mixlo_f16 v4, v19, v6, 0
	ds_write_b16 v18, v4 offset:51328
	v_fma_mixlo_f16 v4, v35, v6, 0
	ds_write_b16 v18, v4 offset:51392
	v_fma_mixlo_f16 v4, v20, v7, 0
	ds_write_b16 v18, v4 offset:51456
	v_fma_mixlo_f16 v4, v36, v7, 0
	ds_write_b16 v18, v4 offset:51520
	v_fma_mixlo_f16 v4, v21, v8, 0
	ds_write_b16 v18, v4 offset:51584
	v_fma_mixlo_f16 v4, v37, v8, 0
	ds_write_b16 v18, v4 offset:51648
	v_fma_mixlo_f16 v4, v22, v9, 0
	ds_write_b16 v18, v4 offset:52224
	v_fma_mixlo_f16 v4, v38, v9, 0
	ds_write_b16 v18, v4 offset:52288
	v_fma_mixlo_f16 v4, v23, v10, 0
	ds_write_b16 v18, v4 offset:52352
	v_fma_mixlo_f16 v4, v39, v10, 0
	ds_write_b16 v18, v4 offset:52416
	v_fma_mixlo_f16 v4, v24, v11, 0
	ds_write_b16 v18, v4 offset:52480
	v_fma_mixlo_f16 v4, v40, v11, 0
	ds_write_b16 v18, v4 offset:52544
	v_fma_mixlo_f16 v4, v25, v12, 0
	ds_write_b16 v18, v4 offset:52608
	v_fma_mixlo_f16 v4, v41, v12, 0
	ds_write_b16 v18, v4 offset:52672
	v_fma_mixlo_f16 v4, v26, v13, 0
	ds_write_b16 v18, v4 offset:53248
	v_fma_mixlo_f16 v4, v42, v13, 0
	ds_write_b16 v18, v4 offset:53312
	v_fma_mixlo_f16 v4, v27, v14, 0
	v_rcp_f32_e32 v66, v177
	s_nop 0
	ds_write_b16 v18, v4 offset:53376
	v_fma_mixlo_f16 v4, v43, v14, 0
	ds_write_b16 v18, v4 offset:53440
	v_fma_mixlo_f16 v4, v28, v15, 0
	ds_write_b16 v18, v4 offset:53504
	v_fma_mixlo_f16 v4, v44, v15, 0
	ds_write_b16 v18, v4 offset:53568
	v_fma_mixlo_f16 v4, v29, v16, 0
	ds_write_b16 v18, v4 offset:53632
	v_fma_mixlo_f16 v4, v45, v16, 0
	s_nop 0
	v_rcp_f32_e32 v2, v178
	ds_write_b16 v18, v4 offset:53696
	v_fma_mixlo_f16 v4, v30, v17, 0
	v_rcp_f32_e32 v3, v179
	ds_write_b16 v18, v4 offset:54272
	v_fma_mixlo_f16 v4, v46, v17, 0
	ds_write_b16 v18, v4 offset:54336
	v_fma_mixlo_f16 v4, v31, v66, 0
	ds_write_b16 v18, v4 offset:54400
	v_fma_mixlo_f16 v4, v47, v66, 0
	ds_write_b16 v18, v4 offset:54464
	v_fma_mixlo_f16 v4, v32, v2, 0
	v_fma_mixlo_f16 v2, v48, v2, 0
	ds_write_b16 v18, v2 offset:54592
	v_fma_mixlo_f16 v2, v33, v3, 0
	s_waitcnt vmcnt(3)
; #define GAS __attribute__((address_space(1)))
; __device__ __forceinline__ float siluf(float x) { return x * __builtin_amdgcn_rcpf(1.f + __builtin_amdgcn_exp2f(-1.4426950408889634f * x)); }
; __device__ __forceinline__ unsigned cvtpk_h(float lo, float hi) { f32x2 v = {lo, hi}; h16x2 b = __builtin_convertvector(v, h16x2); return __builtin_bit_cast(unsigned, b); }
; template <int THRL, bool FIXM> __device__ __forceinline__ bool attn_unit(const h16* Qrows, const h16* __restrict__ Kh, const h16* __restrict__ Vh, const int NT, h16* Yrows, const h16* BZrows, char* shm, const int tid, const float mfix, ...
;     ...
;     asm volatile("s_waitcnt lgkmcnt(0)" ::: "memory");
; #pragma unroll
;     for (int i = 0; i < 4; ++i) { const int row = i * 8 + (lane >> 3), ch = lane & 7; const h16x8 v = *(const h16x8*)(stg + row * 64 + ch * 8); const h16x8 z = zg[i];
;       u32x4 w; w.x = cvtpk_h((float)v[0] * siluf((float)z[0]), (float)v[1] * siluf((float)z[1])); w.y = cvtpk_h((float)v[2] * siluf((float)z[2]), (float)v[3] * siluf((float)z[3]));
;       w.z = cvtpk_h((float)v[4] * siluf((float)z[4]), (float)v[5] * siluf((float)z[5])); w.w = cvtpk_h((float)v[6] * siluf((float)z[6]), (float)v[7] * siluf((float)z[7]));
;       *(GAS u32x4*)(Yw + (long)row * YP + ch * 8) = w; } }
	v_cvt_f32_f16_e32 v8, v62
	ds_write_b16 v18, v2 offset:54656
	v_fma_mixlo_f16 v2, v49, v3, 0
	ds_write_b16 v18, v4 offset:54528
	ds_write_b16 v18, v2 offset:54720
	v_lshrrev_b32_e32 v10, 3, v249
	v_add_u32_e32 v11, s12, v0
	s_waitcnt lgkmcnt(0)
	v_lshl_add_u64 v[6:7], s[10:11], 0, v[0:1]
	v_lshl_add_u32 v0, v10, 7, v11
	ds_read_b128 v[2:5], v0 offset:51200
	v_mul_f32_e32 v0, 0xbfb8aa3b, v8
	v_exp_f32_e32 v0, v0
	v_cvt_f32_f16_sdwa v9, v62 dst_sel:DWORD dst_unused:UNUSED_PAD src0_sel:WORD_1
	s_mov_b64 s[10:11], 0
	s_waitcnt lgkmcnt(0)
	v_cvt_f32_f16_e32 v14, v2
	v_add_f32_e32 v0, 1.0, v0
	v_rcp_f32_e32 v12, v0
	v_mul_f32_e32 v0, 0xbfb8aa3b, v9
	v_exp_f32_e32 v0, v0
	v_cvt_f32_f16_sdwa v15, v2 dst_sel:DWORD dst_unused:UNUSED_PAD src0_sel:WORD_1
	v_add_f32_e32 v0, 1.0, v0
	v_rcp_f32_e32 v13, v0
	s_nop 0
	v_pk_mul_f32 v[8:9], v[12:13], v[8:9]
	s_nop 0
	v_pk_mul_f32 v[8:9], v[8:9], v[14:15]
	v_cvt_f32_f16_e32 v14, v3
	v_cvt_pk_f16_f32 v2, v8, v9
	v_cvt_f32_f16_e32 v8, v63
	v_cvt_f32_f16_sdwa v9, v63 dst_sel:DWORD dst_unused:UNUSED_PAD src0_sel:WORD_1
	v_cvt_f32_f16_sdwa v15, v3 dst_sel:DWORD dst_unused:UNUSED_PAD src0_sel:WORD_1
	v_mul_f32_e32 v0, 0xbfb8aa3b, v8
	v_exp_f32_e32 v0, v0
	s_nop 0
	v_add_f32_e32 v0, 1.0, v0
	v_rcp_f32_e32 v12, v0
	v_mul_f32_e32 v0, 0xbfb8aa3b, v9
	v_exp_f32_e32 v0, v0
	s_nop 0
	v_add_f32_e32 v0, 1.0, v0
	v_rcp_f32_e32 v13, v0
	s_nop 0
	v_pk_mul_f32 v[8:9], v[12:13], v[8:9]
	s_nop 0
	v_pk_mul_f32 v[8:9], v[8:9], v[14:15]
	v_cvt_f32_f16_e32 v14, v4
	v_cvt_pk_f16_f32 v3, v8, v9
	v_cvt_f32_f16_e32 v8, v64
	v_cvt_f32_f16_sdwa v9, v64 dst_sel:DWORD dst_unused:UNUSED_PAD src0_sel:WORD_1
	v_cvt_f32_f16_sdwa v15, v4 dst_sel:DWORD dst_unused:UNUSED_PAD src0_sel:WORD_1
	v_mul_f32_e32 v0, 0xbfb8aa3b, v8
	v_exp_f32_e32 v0, v0
	s_nop 0
	v_add_f32_e32 v0, 1.0, v0
	v_rcp_f32_e32 v12, v0
	v_mul_f32_e32 v0, 0xbfb8aa3b, v9
	v_exp_f32_e32 v0, v0
	s_nop 0
	v_add_f32_e32 v0, 1.0, v0
	v_rcp_f32_e32 v13, v0
	s_nop 0
	v_pk_mul_f32 v[8:9], v[12:13], v[8:9]
	s_nop 0
	v_pk_mul_f32 v[8:9], v[8:9], v[14:15]
	v_cvt_f32_f16_e32 v14, v5
	v_cvt_pk_f16_f32 v4, v8, v9
	v_cvt_f32_f16_e32 v8, v65
	v_cvt_f32_f16_sdwa v9, v65 dst_sel:DWORD dst_unused:UNUSED_PAD src0_sel:WORD_1
	v_cvt_f32_f16_sdwa v15, v5 dst_sel:DWORD dst_unused:UNUSED_PAD src0_sel:WORD_1
	v_mul_f32_e32 v0, 0xbfb8aa3b, v8
	v_exp_f32_e32 v0, v0
	s_nop 0
	v_add_f32_e32 v0, 1.0, v0
	v_rcp_f32_e32 v12, v0
	v_mul_f32_e32 v0, 0xbfb8aa3b, v9
	v_exp_f32_e32 v0, v0
	s_nop 0
	v_add_f32_e32 v0, 1.0, v0
	v_rcp_f32_e32 v13, v0
	v_lshlrev_b32_e32 v0, 11, v10
	v_pk_mul_f32 v[8:9], v[12:13], v[8:9]
	s_nop 0
	v_pk_mul_f32 v[8:9], v[8:9], v[14:15]
	s_nop 0
	v_cvt_pk_f16_f32 v5, v8, v9
	v_lshl_add_u64 v[8:9], v[6:7], 0, v[0:1]
	v_or_b32_e32 v0, 8, v10
	global_store_dwordx4 v[8:9], v[2:5], off offset:512
	s_waitcnt vmcnt(3)
	v_cvt_f32_f16_sdwa v9, v58 dst_sel:DWORD dst_unused:UNUSED_PAD src0_sel:WORD_1
	v_cvt_f32_f16_e32 v8, v58
	v_lshl_add_u32 v2, v0, 7, v11
	ds_read_b128 v[2:5], v2 offset:51200
	v_lshlrev_b32_e32 v0, 11, v0
	v_mul_f32_e32 v12, 0xbfb8aa3b, v8
	v_exp_f32_e32 v12, v12
	s_waitcnt lgkmcnt(0)
	v_cvt_f32_f16_e32 v14, v2
	v_cvt_f32_f16_sdwa v15, v2 dst_sel:DWORD dst_unused:UNUSED_PAD src0_sel:WORD_1
	v_mul_f32_e32 v2, 0xbfb8aa3b, v9
	v_exp_f32_e32 v2, v2
	v_add_f32_e32 v12, 1.0, v12
	v_rcp_f32_e32 v12, v12
	v_add_f32_e32 v2, 1.0, v2
	v_rcp_f32_e32 v13, v2
	s_nop 0
	v_pk_mul_f32 v[8:9], v[12:13], v[8:9]
	s_nop 0
	v_pk_mul_f32 v[8:9], v[8:9], v[14:15]
	v_cvt_f32_f16_e32 v14, v3
	v_cvt_pk_f16_f32 v2, v8, v9
	v_cvt_f32_f16_sdwa v9, v59 dst_sel:DWORD dst_unused:UNUSED_PAD src0_sel:WORD_1
	v_cvt_f32_f16_e32 v8, v59
	v_cvt_f32_f16_sdwa v15, v3 dst_sel:DWORD dst_unused:UNUSED_PAD src0_sel:WORD_1
	v_mul_f32_e32 v3, 0xbfb8aa3b, v9
	v_mul_f32_e32 v12, 0xbfb8aa3b, v8
	v_exp_f32_e32 v12, v12
	v_exp_f32_e32 v3, v3
	v_add_f32_e32 v12, 1.0, v12
	v_add_f32_e32 v3, 1.0, v3
	v_rcp_f32_e32 v12, v12
	v_rcp_f32_e32 v13, v3
	s_nop 0
	v_pk_mul_f32 v[8:9], v[12:13], v[8:9]
	s_nop 0
	v_pk_mul_f32 v[8:9], v[8:9], v[14:15]
	v_cvt_f32_f16_e32 v14, v4
	v_cvt_pk_f16_f32 v3, v8, v9
	v_cvt_f32_f16_sdwa v9, v60 dst_sel:DWORD dst_unused:UNUSED_PAD src0_sel:WORD_1
	v_cvt_f32_f16_e32 v8, v60
	v_cvt_f32_f16_sdwa v15, v4 dst_sel:DWORD dst_unused:UNUSED_PAD src0_sel:WORD_1
	v_mul_f32_e32 v4, 0xbfb8aa3b, v9
	v_mul_f32_e32 v12, 0xbfb8aa3b, v8
	v_exp_f32_e32 v12, v12
	v_exp_f32_e32 v4, v4
	v_add_f32_e32 v12, 1.0, v12
	v_add_f32_e32 v4, 1.0, v4
	v_rcp_f32_e32 v12, v12
	v_rcp_f32_e32 v13, v4
	s_nop 0
	v_pk_mul_f32 v[8:9], v[12:13], v[8:9]
	s_nop 0
	v_pk_mul_f32 v[8:9], v[8:9], v[14:15]
	v_cvt_f32_f16_e32 v14, v5
	v_cvt_pk_f16_f32 v4, v8, v9
	v_cvt_f32_f16_sdwa v9, v61 dst_sel:DWORD dst_unused:UNUSED_PAD src0_sel:WORD_1
	v_cvt_f32_f16_e32 v8, v61
	v_cvt_f32_f16_sdwa v15, v5 dst_sel:DWORD dst_unused:UNUSED_PAD src0_sel:WORD_1
	v_mul_f32_e32 v5, 0xbfb8aa3b, v9
	v_mul_f32_e32 v12, 0xbfb8aa3b, v8
	v_exp_f32_e32 v12, v12
	v_exp_f32_e32 v5, v5
	v_add_f32_e32 v12, 1.0, v12
	v_add_f32_e32 v5, 1.0, v5
	v_rcp_f32_e32 v12, v12
	v_rcp_f32_e32 v13, v5
	s_nop 0
	v_pk_mul_f32 v[8:9], v[12:13], v[8:9]
	s_nop 0
	v_pk_mul_f32 v[8:9], v[8:9], v[14:15]
	s_nop 0
	v_cvt_pk_f16_f32 v5, v8, v9
	v_lshl_add_u64 v[8:9], v[6:7], 0, v[0:1]
	v_or_b32_e32 v0, 16, v10
	global_store_dwordx4 v[8:9], v[2:5], off offset:512
	s_waitcnt vmcnt(3)
; #define GAS __attribute__((address_space(1)))
; __device__ __forceinline__ float siluf(float x) { return x * __builtin_amdgcn_rcpf(1.f + __builtin_amdgcn_exp2f(-1.4426950408889634f * x)); }
; __device__ __forceinline__ unsigned cvtpk_h(float lo, float hi) { f32x2 v = {lo, hi}; h16x2 b = __builtin_convertvector(v, h16x2); return __builtin_bit_cast(unsigned, b); }
; template <int THRL, bool FIXM> __device__ __forceinline__ bool attn_unit(const h16* Qrows, const h16* __restrict__ Kh, const h16* __restrict__ Vh, const int NT, h16* Yrows, const h16* BZrows, char* shm, const int tid, const float mfix, ...
;     ...
;     for (int i = 0; i < 4; ++i) { const int row = i * 8 + (lane >> 3), ch = lane & 7; const h16x8 v = *(const h16x8*)(stg + row * 64 + ch * 8); const h16x8 z = zg[i];
;       u32x4 w; w.x = cvtpk_h((float)v[0] * siluf((float)z[0]), (float)v[1] * siluf((float)z[1])); w.y = cvtpk_h((float)v[2] * siluf((float)z[2]), (float)v[3] * siluf((float)z[3]));
;       w.z = cvtpk_h((float)v[4] * siluf((float)z[4]), (float)v[5] * siluf((float)z[5])); w.w = cvtpk_h((float)v[6] * siluf((float)z[6]), (float)v[7] * siluf((float)z[7]));
;       *(GAS u32x4*)(Yw + (long)row * YP + ch * 8) = w; } }
;   asm volatile("s_waitcnt lgkmcnt(0)\n\ts_barrier" ::: "memory");
	v_cvt_f32_f16_sdwa v9, v54 dst_sel:DWORD dst_unused:UNUSED_PAD src0_sel:WORD_1
	v_cvt_f32_f16_e32 v8, v54
	v_lshl_add_u32 v2, v0, 7, v11
	ds_read_b128 v[2:5], v2 offset:51200
	v_lshlrev_b32_e32 v0, 11, v0
	v_mul_f32_e32 v12, 0xbfb8aa3b, v8
	v_exp_f32_e32 v12, v12
	s_waitcnt lgkmcnt(0)
	v_cvt_f32_f16_e32 v14, v2
	v_cvt_f32_f16_sdwa v15, v2 dst_sel:DWORD dst_unused:UNUSED_PAD src0_sel:WORD_1
	v_mul_f32_e32 v2, 0xbfb8aa3b, v9
	v_exp_f32_e32 v2, v2
	v_add_f32_e32 v12, 1.0, v12
	v_rcp_f32_e32 v12, v12
	v_add_f32_e32 v2, 1.0, v2
	v_rcp_f32_e32 v13, v2
	s_nop 0
	v_pk_mul_f32 v[8:9], v[12:13], v[8:9]
	s_nop 0
	v_pk_mul_f32 v[8:9], v[8:9], v[14:15]
	v_cvt_f32_f16_e32 v14, v3
	v_cvt_pk_f16_f32 v2, v8, v9
	v_cvt_f32_f16_sdwa v9, v55 dst_sel:DWORD dst_unused:UNUSED_PAD src0_sel:WORD_1
	v_cvt_f32_f16_e32 v8, v55
	v_cvt_f32_f16_sdwa v15, v3 dst_sel:DWORD dst_unused:UNUSED_PAD src0_sel:WORD_1
	v_mul_f32_e32 v3, 0xbfb8aa3b, v9
	v_mul_f32_e32 v12, 0xbfb8aa3b, v8
	v_exp_f32_e32 v12, v12
	v_exp_f32_e32 v3, v3
	v_add_f32_e32 v12, 1.0, v12
	v_add_f32_e32 v3, 1.0, v3
	v_rcp_f32_e32 v12, v12
	v_rcp_f32_e32 v13, v3
	s_nop 0
	v_pk_mul_f32 v[8:9], v[12:13], v[8:9]
	s_nop 0
	v_pk_mul_f32 v[8:9], v[8:9], v[14:15]
	v_cvt_f32_f16_e32 v14, v4
	v_cvt_pk_f16_f32 v3, v8, v9
	v_cvt_f32_f16_sdwa v9, v56 dst_sel:DWORD dst_unused:UNUSED_PAD src0_sel:WORD_1
	v_cvt_f32_f16_e32 v8, v56
	v_cvt_f32_f16_sdwa v15, v4 dst_sel:DWORD dst_unused:UNUSED_PAD src0_sel:WORD_1
	v_mul_f32_e32 v4, 0xbfb8aa3b, v9
	v_mul_f32_e32 v12, 0xbfb8aa3b, v8
	v_exp_f32_e32 v12, v12
	v_exp_f32_e32 v4, v4
	v_add_f32_e32 v12, 1.0, v12
	v_add_f32_e32 v4, 1.0, v4
	v_rcp_f32_e32 v12, v12
	v_rcp_f32_e32 v13, v4
	s_nop 0
	v_pk_mul_f32 v[8:9], v[12:13], v[8:9]
	s_nop 0
	v_pk_mul_f32 v[8:9], v[8:9], v[14:15]
	v_cvt_f32_f16_e32 v14, v5
	v_cvt_pk_f16_f32 v4, v8, v9
	v_cvt_f32_f16_sdwa v9, v57 dst_sel:DWORD dst_unused:UNUSED_PAD src0_sel:WORD_1
	v_cvt_f32_f16_e32 v8, v57
	v_cvt_f32_f16_sdwa v15, v5 dst_sel:DWORD dst_unused:UNUSED_PAD src0_sel:WORD_1
	v_mul_f32_e32 v5, 0xbfb8aa3b, v9
	v_mul_f32_e32 v12, 0xbfb8aa3b, v8
	v_exp_f32_e32 v12, v12
	v_exp_f32_e32 v5, v5
	v_add_f32_e32 v12, 1.0, v12
	v_add_f32_e32 v5, 1.0, v5
	v_rcp_f32_e32 v12, v12
	v_rcp_f32_e32 v13, v5
	s_nop 0
	v_pk_mul_f32 v[8:9], v[12:13], v[8:9]
	s_nop 0
	v_pk_mul_f32 v[8:9], v[8:9], v[14:15]
	s_nop 0
	v_cvt_pk_f16_f32 v5, v8, v9
	v_lshl_add_u64 v[8:9], v[6:7], 0, v[0:1]
	v_or_b32_e32 v0, 24, v10
	global_store_dwordx4 v[8:9], v[2:5], off offset:512
	s_waitcnt vmcnt(3)
	v_cvt_f32_f16_sdwa v9, v50 dst_sel:DWORD dst_unused:UNUSED_PAD src0_sel:WORD_1
	v_cvt_f32_f16_e32 v8, v50
	v_lshl_add_u32 v2, v0, 7, v11
	ds_read_b128 v[2:5], v2 offset:51200
	v_lshlrev_b32_e32 v0, 11, v0
	v_mul_f32_e32 v10, 0xbfb8aa3b, v8
	v_exp_f32_e32 v10, v10
	v_lshl_add_u64 v[6:7], v[6:7], 0, v[0:1]
	s_waitcnt lgkmcnt(0)
	v_cvt_f32_f16_e32 v12, v2
	v_cvt_f32_f16_sdwa v13, v2 dst_sel:DWORD dst_unused:UNUSED_PAD src0_sel:WORD_1
	v_mul_f32_e32 v2, 0xbfb8aa3b, v9
	v_exp_f32_e32 v2, v2
	v_add_f32_e32 v10, 1.0, v10
	v_rcp_f32_e32 v10, v10
	v_add_f32_e32 v2, 1.0, v2
	v_rcp_f32_e32 v11, v2
	s_nop 0
	v_pk_mul_f32 v[8:9], v[10:11], v[8:9]
	s_nop 0
	v_pk_mul_f32 v[8:9], v[8:9], v[12:13]
	v_cvt_f32_f16_e32 v12, v3
	v_cvt_pk_f16_f32 v2, v8, v9
	v_cvt_f32_f16_sdwa v9, v51 dst_sel:DWORD dst_unused:UNUSED_PAD src0_sel:WORD_1
	v_cvt_f32_f16_e32 v8, v51
	v_cvt_f32_f16_sdwa v13, v3 dst_sel:DWORD dst_unused:UNUSED_PAD src0_sel:WORD_1
	v_mul_f32_e32 v3, 0xbfb8aa3b, v9
	v_mul_f32_e32 v10, 0xbfb8aa3b, v8
	v_exp_f32_e32 v10, v10
	v_exp_f32_e32 v3, v3
	v_add_f32_e32 v10, 1.0, v10
	v_add_f32_e32 v3, 1.0, v3
	v_rcp_f32_e32 v10, v10
	v_rcp_f32_e32 v11, v3
	s_nop 0
	v_pk_mul_f32 v[8:9], v[10:11], v[8:9]
	s_nop 0
	v_pk_mul_f32 v[8:9], v[8:9], v[12:13]
	v_cvt_f32_f16_e32 v12, v4
	v_cvt_pk_f16_f32 v3, v8, v9
	v_cvt_f32_f16_sdwa v9, v52 dst_sel:DWORD dst_unused:UNUSED_PAD src0_sel:WORD_1
	v_cvt_f32_f16_e32 v8, v52
	v_cvt_f32_f16_sdwa v13, v4 dst_sel:DWORD dst_unused:UNUSED_PAD src0_sel:WORD_1
	v_mul_f32_e32 v4, 0xbfb8aa3b, v9
	v_mul_f32_e32 v10, 0xbfb8aa3b, v8
	v_exp_f32_e32 v10, v10
	v_exp_f32_e32 v4, v4
	v_add_f32_e32 v10, 1.0, v10
	v_add_f32_e32 v4, 1.0, v4
	v_rcp_f32_e32 v10, v10
	v_rcp_f32_e32 v11, v4
	s_nop 0
	v_pk_mul_f32 v[8:9], v[10:11], v[8:9]
	s_nop 0
	v_pk_mul_f32 v[8:9], v[8:9], v[12:13]
	v_cvt_f32_f16_e32 v12, v5
	v_cvt_pk_f16_f32 v4, v8, v9
	v_cvt_f32_f16_sdwa v9, v53 dst_sel:DWORD dst_unused:UNUSED_PAD src0_sel:WORD_1
	v_cvt_f32_f16_e32 v8, v53
	v_cvt_f32_f16_sdwa v13, v5 dst_sel:DWORD dst_unused:UNUSED_PAD src0_sel:WORD_1
	v_mul_f32_e32 v5, 0xbfb8aa3b, v9
	v_mul_f32_e32 v10, 0xbfb8aa3b, v8
	v_exp_f32_e32 v10, v10
	v_exp_f32_e32 v5, v5
	v_add_f32_e32 v10, 1.0, v10
	v_add_f32_e32 v5, 1.0, v5
	v_rcp_f32_e32 v10, v10
	v_rcp_f32_e32 v11, v5
	s_nop 0
	v_pk_mul_f32 v[8:9], v[10:11], v[8:9]
	s_nop 0
	v_pk_mul_f32 v[8:9], v[8:9], v[12:13]
	s_nop 0
	v_cvt_pk_f16_f32 v5, v8, v9
	global_store_dwordx4 v[6:7], v[2:5], off offset:512
	s_waitcnt lgkmcnt(0)
	s_barrier
